# ping-pong attention: row-sum adds moved from the compute segment to the next load segment (P fragments written to dead K-fragment registers)
# baseline (speedup 1.0000x reference)
; DI void attn_unit(const Params& p, LAS unsigned char* ldsu, int kind, int b, int h, int u, float lam) {
;     ...
;     f32x16 O[4]; float l = 0.f;
; #pragma unroll
;     for (int v = 0; v < 4; ++v)
; #pragma unroll
;         for (int i = 0; i < 16; ++i) O[v][i] = 0.f;
;     const int i16 = lane & 15, q4 = i16 >> 2, p4 = i16 & 3, blk = (lane >> 4) & 1;
;     const int kboff = qr * KRS + 16 * hh + cmp * 128, vboff = SLOT_V + (4 * hh + q4) * VRS + blk * 32 + p4 * 8;
;     ...
;     if (kind == 0) {
;         unsigned poff[5]; dma_offsets(poff, wid, lane);
;         auto stage = [&](int t) { if (t >= ntl) t = ntl - 1; const int row0 = t == 0 ? ROW_M : b * SEQ + (t - 1) * 64;
;             dma_tile(lds + (t & 3) * SLOT_B, KB + (size_t)row0 * 512 + hc, VB + (size_t)row0 * 512 + hc, poff, wid); };
;         stage(0); stage(1); stage(2);
;         asm volatile("s_waitcnt vmcnt(10)" ::: "memory");
;         __syncthreads();
.LBB0_743:
	s_add_i32 s6, s31, -1
	v_readlane_b32 s7, v254, 22
	s_add_u32 s22, s7, s62
	v_readlane_b32 s7, v254, 23
	s_addc_u32 s23, s7, 0
	v_readlane_b32 s7, v254, 24
	s_add_u32 s24, s7, s62
	v_readlane_b32 s7, v254, 25
	s_addc_u32 s25, s7, 0
	s_and_b64 s[10:11], s[0:1], exec
	v_lshlrev_b32_e32 v0, 10, v0
	v_min_i32_e32 v2, 15, v2
	s_cselect_b32 s21, s23, s25
	s_cselect_b32 s20, s22, s24
	s_lshl_b32 s7, s12, 10
	v_lshl_or_b32 v132, v2, 4, v0
	s_add_i32 s26, s7, 0
	s_mov_b32 s10, m0
	s_mov_b32 m0, s26
	s_nop 0
	global_load_lds_dwordx4 v132, s[20:21]
	s_mov_b32 m0, s10
	s_lshl_b32 s10, s13, 10
	s_add_i32 s27, s10, 0
	s_add_i32 s11, s27, 0x400
	v_lshlrev_b32_e32 v3, 10, v3
	v_min_i32_e32 v4, 15, v4
	s_and_b64 s[12:13], exec, s[8:9]
	v_lshl_or_b32 v131, v4, 4, v3
	s_mov_b32 s12, m0
	s_mov_b32 m0, s11
	s_nop 0
	global_load_lds_dwordx4 v131, s[20:21]
	s_mov_b32 m0, s12
	s_cselect_b32 s21, s23, s25
	s_cselect_b32 s20, s22, s24
	s_lshl_b32 s11, s18, 10
	s_add_i32 s22, s11, 0
	v_lshlrev_b32_e32 v5, 10, v5
	v_min_i32_e32 v6, 15, v6
	s_add_i32 s12, s22, 0x800
	v_lshl_or_b32 v130, v6, 4, v5
	s_mov_b32 s13, m0
	s_mov_b32 m0, s12
	s_nop 0
	global_load_lds_dwordx4 v130, s[20:21]
	s_mov_b32 m0, s13
	s_lshl_b32 s12, s19, 10
	s_add_i32 s23, s12, 0
	v_lshlrev_b32_e32 v7, 10, v7
	v_min_i32_e32 v8, 15, v8
	s_add_i32 s13, s23, 0xc00
	v_lshl_or_b32 v129, v8, 4, v7
	s_mov_b32 s18, m0
	s_mov_b32 m0, s13
	s_nop 0
	global_load_lds_dwordx4 v129, s[20:21]
	s_mov_b32 m0, s18
	s_lshl_b32 s13, s17, 10
	s_add_i32 s24, s13, 0
	v_lshlrev_b32_e32 v0, 10, v9
	v_min_i32_e32 v2, 15, v10
	s_add_i32 s17, s24, 0x1000
	v_lshl_or_b32 v133, v2, 4, v0
	s_mov_b32 s18, m0
	s_mov_b32 m0, s17
	s_nop 0
	global_load_lds_dwordx4 v133, s[20:21]
	s_mov_b32 m0, s18
	s_lshl_b32 s17, s16, 12
	s_sub_i32 s17, s17, 64
	s_lshl_b32 s16, s16, 22
	v_readlane_b32 s36, v254, 14
	s_add_u32 s18, s36, s16
	v_readlane_b32 s37, v254, 15
	s_addc_u32 s19, s37, 0
	s_add_u32 s20, s18, s62
	s_addc_u32 s21, s19, 0
	v_readlane_b32 s38, v254, 16
	s_add_u32 s18, s38, s16
	v_readlane_b32 s39, v254, 17
	s_addc_u32 s19, s39, 0
	s_add_u32 s25, s18, s62
	s_addc_u32 s34, s19, 0
	s_and_b64 s[18:19], s[0:1], exec
	s_cselect_b32 s19, s21, s34
	s_cselect_b32 s18, s20, s25
	s_add_i32 s26, s26, 0x9400
	s_mov_b32 s35, m0
	s_mov_b32 m0, s26
	s_nop 0
	global_load_lds_dwordx4 v132, s[18:19]
	s_mov_b32 m0, s35
	s_add_i32 s27, s27, 0x9800
	s_mov_b32 s26, m0
	s_mov_b32 m0, s27
	s_nop 0
	global_load_lds_dwordx4 v131, s[18:19]
	s_mov_b32 m0, s26
	s_and_b64 s[18:19], exec, s[8:9]
	s_cselect_b32 s19, s21, s34
	s_cselect_b32 s18, s20, s25
	s_add_i32 s22, s22, 0x9c00
	s_mov_b32 s20, m0
	s_mov_b32 m0, s22
	s_nop 0
	global_load_lds_dwordx4 v130, s[18:19]
	s_mov_b32 m0, s20
	s_add_i32 s23, s23, 0xa000
	s_mov_b32 s20, m0
	s_mov_b32 m0, s23
	s_nop 0
	global_load_lds_dwordx4 v129, s[18:19]
	s_mov_b32 m0, s20
	s_add_i32 s24, s24, 0xa400
	s_bitset1_b32 s16, 16
	s_mov_b32 s20, m0
	s_mov_b32 m0, s24
	s_nop 0
	global_load_lds_dwordx4 v133, s[18:19]
	s_mov_b32 m0, s20
	s_add_u32 s18, s36, s16
	s_addc_u32 s19, s37, 0
	s_add_u32 s20, s18, s62
	s_addc_u32 s21, s19, 0
	s_add_u32 s16, s38, s16
	s_addc_u32 s18, s39, 0
	s_add_u32 s16, s16, s62
	s_addc_u32 s22, s18, 0
	s_and_b64 s[18:19], s[0:1], exec
	v_readlane_b32 s25, v254, 30
	s_cselect_b32 s19, s21, s22
	s_cselect_b32 s18, s20, s16
	s_add_i32 s23, s25, s7
	s_mov_b32 s24, m0
	s_mov_b32 m0, s23
	s_nop 0
	global_load_lds_dwordx4 v132, s[18:19]
	s_mov_b32 m0, s24
	s_add_i32 s23, s25, s10
	s_addk_i32 s23, 0x400
	s_mov_b32 s24, m0
	s_mov_b32 m0, s23
	s_nop 0
	global_load_lds_dwordx4 v131, s[18:19]
	s_mov_b32 m0, s24
	s_and_b64 s[18:19], exec, s[8:9]
	s_cselect_b32 s19, s21, s22
	s_cselect_b32 s18, s20, s16
	s_add_i32 s16, s25, s11
	s_addk_i32 s16, 0x800
	s_mov_b32 s20, m0
	s_mov_b32 m0, s16
	s_nop 0
	global_load_lds_dwordx4 v130, s[18:19]
	s_mov_b32 m0, s20
	s_add_i32 s16, s25, s12
	s_addk_i32 s16, 0xc00
	s_mov_b32 s20, m0
	s_mov_b32 m0, s16
	s_nop 0
	global_load_lds_dwordx4 v129, s[18:19]
	s_mov_b32 m0, s20
	s_add_i32 s16, s25, s13
	s_addk_i32 s16, 0x1000
	s_mov_b32 s20, m0
	s_mov_b32 m0, s16
	s_nop 0
	global_load_lds_dwordx4 v133, s[18:19]
	s_mov_b32 m0, s20
	s_add_u32 s16, s36, s62
	s_waitcnt vmcnt(10)
	s_addc_u32 s18, s37, 0
	v_mov_b32_e32 v14, v1
	v_mov_b32_e32 v15, v1
	s_add_u32 s19, s38, s62
	v_mov_b32_e32 v0, v1
	v_mov_b32_e32 v2, v1
	v_mov_b32_e32 v3, v1
	v_mov_b32_e32 v4, v1
	v_mov_b32_e32 v5, v1
	v_mov_b32_e32 v6, v1
	v_mov_b32_e32 v7, v1
	v_mov_b32_e32 v8, v1
	v_mov_b32_e32 v9, v1
	v_mov_b32_e32 v10, v1
	v_mov_b32_e32 v11, v1
	v_mov_b32_e32 v12, v1
	v_mov_b32_e32 v13, v1
	v_mov_b64_e32 v[30:31], v[14:15]
	v_mov_b64_e32 v[46:47], v[14:15]
	v_mov_b64_e32 v[62:63], v[14:15]
	v_mov_b64_e32 v[78:79], v[14:15]
	s_addc_u32 s20, s39, 0
	v_add3_u32 v134, v176, v177, v178
	s_mov_b32 s21, 0
	v_mov_b32_e32 v175, 0
	v_mov_b64_e32 v[28:29], v[12:13]
	v_mov_b64_e32 v[26:27], v[10:11]
	v_mov_b64_e32 v[24:25], v[8:9]
	v_mov_b64_e32 v[22:23], v[6:7]
	v_mov_b64_e32 v[20:21], v[4:5]
	v_mov_b64_e32 v[18:19], v[2:3]
	v_mov_b64_e32 v[16:17], v[0:1]
	v_mov_b64_e32 v[44:45], v[12:13]
	v_mov_b64_e32 v[42:43], v[10:11]
	v_mov_b64_e32 v[40:41], v[8:9]
	v_mov_b64_e32 v[38:39], v[6:7]
	v_mov_b64_e32 v[36:37], v[4:5]
	v_mov_b64_e32 v[34:35], v[2:3]
	v_mov_b64_e32 v[32:33], v[0:1]
	v_mov_b64_e32 v[60:61], v[12:13]
	v_mov_b64_e32 v[58:59], v[10:11]
	v_mov_b64_e32 v[56:57], v[8:9]
	v_mov_b64_e32 v[54:55], v[6:7]
	v_mov_b64_e32 v[52:53], v[4:5]
	v_mov_b64_e32 v[50:51], v[2:3]
	v_mov_b64_e32 v[48:49], v[0:1]
	v_mov_b64_e32 v[76:77], v[12:13]
	v_mov_b64_e32 v[74:75], v[10:11]
	v_mov_b64_e32 v[72:73], v[8:9]
	v_mov_b64_e32 v[70:71], v[6:7]
	v_mov_b64_e32 v[68:69], v[4:5]
	v_mov_b64_e32 v[66:67], v[2:3]
	v_mov_b64_e32 v[64:65], v[0:1]
	s_waitcnt lgkmcnt(0)
	s_barrier
	v_mov_b64_e32 v[80:81], v[0:1]
	v_mov_b64_e32 v[82:83], v[0:1]
	v_mov_b64_e32 v[84:85], v[0:1]
	v_mov_b64_e32 v[86:87], v[0:1]
	v_mov_b64_e32 v[88:89], v[0:1]
	v_mov_b64_e32 v[90:91], v[0:1]
	v_mov_b64_e32 v[92:93], v[0:1]
	v_mov_b64_e32 v[94:95], v[0:1]
	v_mov_b64_e32 v[96:97], v[0:1]
	v_mov_b64_e32 v[98:99], v[0:1]
	v_mov_b64_e32 v[100:101], v[0:1]
	v_mov_b64_e32 v[102:103], v[0:1]
	v_mov_b64_e32 v[104:105], v[0:1]
	v_mov_b64_e32 v[106:107], v[0:1]
	v_mov_b64_e32 v[108:109], v[0:1]
	v_mov_b64_e32 v[110:111], v[0:1]
	s_and_b64 vcc, exec, s[0:1]
	s_cbranch_vccnz .LBB0_745
	s_barrier
	s_branch .LBB0_745

; #define LAS __attribute__((address_space(3)))
; DI void attn_qk(const LAS char* kb, const bf16x8 (&qf)[4], bf16x8 (&pf)[4], float& l) {
;     ...
;     float sum = 0.f;
; #pragma unroll
;     for (int i = 0; i < 16; ++i) { const float e = __builtin_amdgcn_exp2f(st0[i]); st0[i] = e; sum += e; }
;     pf[0] = pack8(st0, 0); pf[1] = pack8(st0, 1);
; #pragma unroll
;     for (int i = 0; i < 16; ++i) { const float e = __builtin_amdgcn_exp2f(st1[i]); st1[i] = e; sum += e; }
;     pf[2] = pack8(st1, 0); pf[3] = pack8(st1, 1);
;     l += sum;
; DI void attn_unit(const Params& p, LAS unsigned char* ldsu, int kind, int b, int h, int u, float lam) {
;     ...
;         for (int t = 0; t < ntl; ++t) {
;             stage(t + 3);
;             const LAS char* sp = lds + (t & 3) * SLOT_B;
;             if (t <= my_last) { bf16x8 pf[4]; attn_qk(sp + kboff, qf, pf, l); attn_pv(sp + vboff, pf, O); }
.LBB0_745:
	s_and_b64 vcc, exec, s[0:1]
	s_cbranch_vccz .LattnB
	s_add_i32 s22, s21, 3
	s_min_i32 s24, s22, s6
	s_lshl_b32 s22, s24, 6
	s_add_i32 s22, s17, s22
	s_and_b32 s24, s24, 3
	s_ashr_i32 s23, s22, 31
	s_mul_i32 s24, s24, 0x9400
	s_lshl_b64 s[22:23], s[22:23], 10
	s_add_u32 s25, s16, s22
	s_addc_u32 s26, s18, s23
	s_add_u32 s27, s19, s22
	s_addc_u32 s34, s20, s23
	s_cmp_gt_i32 s21, s29
	s_cbranch_scc1 .LattnA_skip
	s_and_b32 s35, s21, 3
	s_mul_i32 s35, s35, 0x9400
	v_add_u32_e32 v0, s35, v174
	v_add_u32_e32 v14, s35, v134
	ds_read_b128 v[2:5], v0
	ds_read_b128 v[6:9], v0 offset:32
	ds_read_b128 v[10:13], v0 offset:64
	ds_read_b128 v[136:139], v0 offset:96
	ds_read_b128 v[140:143], v0 offset:8704
	ds_read_b128 v[144:147], v0 offset:8736
	ds_read_b128 v[148:151], v0 offset:8768
	ds_read_b128 v[196:199], v0 offset:8800
	ds_read_b64_tr_b16 v[200:201], v14 offset:17408
	ds_read_b64_tr_b16 v[202:203], v14 offset:19968
	ds_read_b64_tr_b16 v[204:205], v14 offset:17472
	ds_read_b64_tr_b16 v[206:207], v14 offset:20032
	ds_read_b64_tr_b16 v[208:209], v14 offset:17536
	ds_read_b64_tr_b16 v[210:211], v14 offset:20096
	ds_read_b64_tr_b16 v[212:213], v14 offset:17600
	ds_read_b64_tr_b16 v[214:215], v14 offset:20160
	ds_read_b64_tr_b16 v[216:217], v14 offset:22528
	ds_read_b64_tr_b16 v[218:219], v14 offset:25088
	ds_read_b64_tr_b16 v[220:221], v14 offset:22592
	ds_read_b64_tr_b16 v[222:223], v14 offset:25152
	ds_read_b64_tr_b16 v[224:225], v14 offset:22656
	ds_read_b64_tr_b16 v[226:227], v14 offset:25216
	ds_read_b64_tr_b16 v[228:229], v14 offset:22720
	ds_read_b64_tr_b16 v[230:231], v14 offset:25280
	ds_read_b64_tr_b16 v[232:233], v14 offset:27648
	ds_read_b64_tr_b16 v[234:235], v14 offset:30208
	ds_read_b64_tr_b16 v[236:237], v14 offset:27712
	ds_read_b64_tr_b16 v[238:239], v14 offset:30272
	ds_read_b64_tr_b16 v[240:241], v14 offset:27776
	ds_read_b64_tr_b16 v[242:243], v14 offset:30336
	ds_read_b64_tr_b16 v[244:245], v14 offset:27840
	ds_read_b64_tr_b16 v[246:247], v14 offset:30400
	ds_read_b64_tr_b16 v[248:249], v14 offset:32768
	ds_read_b64_tr_b16 v[250:251], v14 offset:35328
	ds_read_b64_tr_b16 v[156:157], v14 offset:32832
	ds_read_b64_tr_b16 v[158:159], v14 offset:35392
	ds_read_b64_tr_b16 v[160:161], v14 offset:32896
	ds_read_b64_tr_b16 v[162:163], v14 offset:35456
	ds_read_b64_tr_b16 v[164:165], v14 offset:32960
	ds_read_b64_tr_b16 v[166:167], v14 offset:35520
	s_and_b64 s[22:23], s[0:1], exec
	s_cselect_b32 s23, s26, s34
	s_cselect_b32 s22, s25, s27
	s_add_i32 s35, s24, s7
	s_mov_b32 m0, s35
	s_nop 0
	global_load_lds_dwordx4 v132, s[22:23]
	s_add_i32 s35, s24, s10
	s_addk_i32 s35, 0x400
	s_mov_b32 m0, s35
	s_nop 0
	global_load_lds_dwordx4 v131, s[22:23]
	s_and_b64 s[22:23], exec, s[8:9]
	s_cselect_b32 s23, s26, s34
	s_cselect_b32 s22, s25, s27
	s_add_i32 s35, s24, s11
	s_addk_i32 s35, 0x800
	s_mov_b32 m0, s35
	s_nop 0
	global_load_lds_dwordx4 v130, s[22:23]
	s_add_i32 s35, s24, s12
	s_addk_i32 s35, 0xc00
	s_mov_b32 m0, s35
	s_nop 0
	global_load_lds_dwordx4 v129, s[22:23]
	s_add_i32 s35, s24, s13
	s_addk_i32 s35, 0x1000
	s_mov_b32 m0, s35
	s_nop 0
	global_load_lds_dwordx4 v133, s[22:23]
	v_add_f32_e32 v15, v96, v97
	v_add_f32_e32 v15, v98, v15
	v_add_f32_e32 v15, v99, v15
	v_add_f32_e32 v15, v100, v15
	v_add_f32_e32 v15, v101, v15
	v_add_f32_e32 v15, v102, v15
	v_add_f32_e32 v15, v103, v15
	v_add_f32_e32 v15, v104, v15
	v_add_f32_e32 v15, v105, v15
	v_add_f32_e32 v15, v106, v15
	v_add_f32_e32 v15, v107, v15
	v_add_f32_e32 v15, v108, v15
	v_add_f32_e32 v15, v109, v15
	v_add_f32_e32 v15, v110, v15
	v_add_f32_e32 v15, v111, v15
	v_add_f32_e32 v15, v80, v15
	v_add_f32_e32 v15, v81, v15
	v_add_f32_e32 v15, v82, v15
	v_add_f32_e32 v15, v83, v15
	v_add_f32_e32 v15, v84, v15
	v_add_f32_e32 v15, v85, v15
	v_add_f32_e32 v15, v86, v15
	v_add_f32_e32 v15, v87, v15
	v_add_f32_e32 v15, v88, v15
	v_add_f32_e32 v15, v89, v15
	v_add_f32_e32 v15, v90, v15
	v_add_f32_e32 v15, v91, v15
	v_add_f32_e32 v15, v92, v15
	v_add_f32_e32 v15, v93, v15
	v_add_f32_e32 v15, v94, v15
	v_add_f32_e32 v15, v95, v15
	v_add_f32_e32 v175, v175, v15
	s_waitcnt lgkmcnt(0)
	s_barrier
; #define LAS __attribute__((address_space(3)))
; DI s16x4 vtr(const LAS char* p) { return __builtin_bit_cast(s16x4, __builtin_amdgcn_ds_read_tr16_b64_v4i16((LAS v4i16_t*)p)); }
; DI bf16x8 cat4(s16x4 lo, s16x4 hi) { return __builtin_shufflevector(lo, hi, 0, 1, 2, 3, 4, 5, 6, 7); }
; #define SGB(mask, n) __builtin_amdgcn_sched_group_barrier((mask), (n), 0)
; DI void attn_qk(const LAS char* kb, const bf16x8 (&qf)[4], bf16x8 (&pf)[4], float& l) {
;     ...
;     f32x16 st0 = MFMA32(k0[0], qf[0], zero), st1 = MFMA32(k1[0], qf[0], zero);
; #pragma unroll
;     for (int s = 1; s < 4; ++s) { st0 = MFMA32(k0[s], qf[s], st0); st1 = MFMA32(k1[s], qf[s], st1); }
;     SGB(0x100, 8); SGB(0x008, 8);
;     float sum = 0.f;
; #pragma unroll
;     for (int i = 0; i < 16; ++i) { const float e = __builtin_amdgcn_exp2f(st0[i]); st0[i] = e; sum += e; }
;     pf[0] = pack8(st0, 0); pf[1] = pack8(st0, 1);
; #pragma unroll
;     for (int i = 0; i < 16; ++i) { const float e = __builtin_amdgcn_exp2f(st1[i]); st1[i] = e; sum += e; }
;     pf[2] = pack8(st1, 0); pf[3] = pack8(st1, 1);
;     l += sum;
; }
; DI void attn_pv(const LAS char* vb, const bf16x8 (&pf)[4], f32x16 (&O)[4]) {
;     s16x4 va[8], vc[8];
; #pragma unroll
;     for (int ks = 0; ks < 4; ++ks) { va[2 * ks] = vtr(vb + ks * 16 * VRS); va[2 * ks + 1] = vtr(vb + (ks * 16 + 8) * VRS); }
; #pragma unroll
;     for (int ks = 0; ks < 4; ++ks) { vc[2 * ks] = vtr(vb + ks * 16 * VRS + 64); vc[2 * ks + 1] = vtr(vb + (ks * 16 + 8) * VRS + 64); }
; #pragma unroll
;     for (int ks = 0; ks < 4; ++ks) O[0] = MFMA32(cat4(va[2 * ks], va[2 * ks + 1]), pf[ks], O[0]);
; #pragma unroll
;     for (int ks = 0; ks < 4; ++ks) { va[2 * ks] = vtr(vb + ks * 16 * VRS + 128); va[2 * ks + 1] = vtr(vb + (ks * 16 + 8) * VRS + 128); }
;     SGB(0x100, 16); SGB(0x008, 4); SGB(0x100, 8);
; #pragma unroll
;     for (int ks = 0; ks < 4; ++ks) O[1] = MFMA32(cat4(vc[2 * ks], vc[2 * ks + 1]), pf[ks], O[1]);
; #pragma unroll
;     for (int ks = 0; ks < 4; ++ks) { vc[2 * ks] = vtr(vb + ks * 16 * VRS + 192); vc[2 * ks + 1] = vtr(vb + (ks * 16 + 8) * VRS + 192); }
;     SGB(0x008, 4); SGB(0x100, 8);
; #pragma unroll
;     for (int ks = 0; ks < 4; ++ks) O[2] = MFMA32(cat4(va[2 * ks], va[2 * ks + 1]), pf[ks], O[2]);
;     SGB(0x008, 4);
; #pragma unroll
;     for (int ks = 0; ks < 4; ++ks) O[3] = MFMA32(cat4(vc[2 * ks], vc[2 * ks + 1]), pf[ks], O[3]);
;     SGB(0x008, 4);
	v_mfma_f32_32x32x16_bf16 v[96:111], v[2:5], v[112:115], 0
	v_mfma_f32_32x32x16_bf16 v[96:111], v[6:9], v[116:119], v[96:111]
	v_mfma_f32_32x32x16_bf16 v[96:111], v[10:13], v[120:123], v[96:111]
	v_mfma_f32_32x32x16_bf16 v[96:111], v[136:139], v[124:127], v[96:111]
	s_nop 7
	s_nop 2
	v_mfma_f32_32x32x16_bf16 v[80:95], v[140:143], v[112:115], 0
	v_exp_f32_e32 v96, v96
	v_exp_f32_e32 v97, v97
	v_mfma_f32_32x32x16_bf16 v[80:95], v[144:147], v[116:119], v[80:95]
	v_exp_f32_e32 v98, v98
	v_exp_f32_e32 v99, v99
	v_cvt_pk_bf16_f32 v2, v96, v97
	v_mfma_f32_32x32x16_bf16 v[80:95], v[148:151], v[120:123], v[80:95]
	v_exp_f32_e32 v100, v100
	v_exp_f32_e32 v101, v101
	v_cvt_pk_bf16_f32 v3, v98, v99
	v_mfma_f32_32x32x16_bf16 v[80:95], v[196:199], v[124:127], v[80:95]
	v_exp_f32_e32 v102, v102
	v_exp_f32_e32 v103, v103
	v_cvt_pk_bf16_f32 v4, v100, v101
	v_cvt_pk_bf16_f32 v5, v102, v103
	s_nop 1
	v_mfma_f32_32x32x16_bf16 v[64:79], v[200:203], v[2:5], v[64:79]
	v_exp_f32_e32 v104, v104
	v_exp_f32_e32 v105, v105
	v_mfma_f32_32x32x16_bf16 v[48:63], v[204:207], v[2:5], v[48:63]
	v_exp_f32_e32 v106, v106
	v_exp_f32_e32 v107, v107
	v_cvt_pk_bf16_f32 v6, v104, v105
	v_mfma_f32_32x32x16_bf16 v[32:47], v[208:211], v[2:5], v[32:47]
	v_exp_f32_e32 v108, v108
	v_exp_f32_e32 v109, v109
	v_cvt_pk_bf16_f32 v7, v106, v107
	v_mfma_f32_32x32x16_bf16 v[16:31], v[212:215], v[2:5], v[16:31]
	v_exp_f32_e32 v110, v110
	v_exp_f32_e32 v111, v111
	v_cvt_pk_bf16_f32 v8, v108, v109
	v_cvt_pk_bf16_f32 v9, v110, v111
	s_nop 1
	v_mfma_f32_32x32x16_bf16 v[64:79], v[216:219], v[6:9], v[64:79]
	v_exp_f32_e32 v80, v80
	v_exp_f32_e32 v81, v81
	v_mfma_f32_32x32x16_bf16 v[48:63], v[220:223], v[6:9], v[48:63]
	v_exp_f32_e32 v82, v82
	v_exp_f32_e32 v83, v83
	v_cvt_pk_bf16_f32 v140, v80, v81
	v_mfma_f32_32x32x16_bf16 v[32:47], v[224:227], v[6:9], v[32:47]
	v_exp_f32_e32 v84, v84
	v_exp_f32_e32 v85, v85
	v_cvt_pk_bf16_f32 v141, v82, v83
	v_mfma_f32_32x32x16_bf16 v[16:31], v[228:231], v[6:9], v[16:31]
	v_exp_f32_e32 v86, v86
	v_exp_f32_e32 v87, v87
	v_cvt_pk_bf16_f32 v142, v84, v85
	v_cvt_pk_bf16_f32 v143, v86, v87
	s_nop 1
	v_mfma_f32_32x32x16_bf16 v[64:79], v[232:235], v[140:143], v[64:79]
	v_exp_f32_e32 v88, v88
	v_exp_f32_e32 v89, v89
	v_mfma_f32_32x32x16_bf16 v[48:63], v[236:239], v[140:143], v[48:63]
	v_exp_f32_e32 v90, v90
	v_exp_f32_e32 v91, v91
	v_cvt_pk_bf16_f32 v144, v88, v89
	v_mfma_f32_32x32x16_bf16 v[32:47], v[240:243], v[140:143], v[32:47]
	v_exp_f32_e32 v92, v92
	v_exp_f32_e32 v93, v93
	v_cvt_pk_bf16_f32 v145, v90, v91
	v_mfma_f32_32x32x16_bf16 v[16:31], v[244:247], v[140:143], v[16:31]
	v_exp_f32_e32 v94, v94
	v_exp_f32_e32 v95, v95
	v_cvt_pk_bf16_f32 v146, v92, v93
	v_cvt_pk_bf16_f32 v147, v94, v95
	s_nop 1
	v_mfma_f32_32x32x16_bf16 v[64:79], v[248:251], v[144:147], v[64:79]
	v_mfma_f32_32x32x16_bf16 v[48:63], v[156:159], v[144:147], v[48:63]
	v_mfma_f32_32x32x16_bf16 v[32:47], v[160:163], v[144:147], v[32:47]
	v_mfma_f32_32x32x16_bf16 v[16:31], v[164:167], v[144:147], v[16:31]
	s_waitcnt vmcnt(10)
	s_barrier
	s_branch .LBB0_744

; #define LAS __attribute__((address_space(3)))
; DI void attn_qk(const LAS char* kb, const bf16x8 (&qf)[4], bf16x8 (&pf)[4], float& l) {
;     ...
;     float sum = 0.f;
; #pragma unroll
;     for (int i = 0; i < 16; ++i) { const float e = __builtin_amdgcn_exp2f(st0[i]); st0[i] = e; sum += e; }
;     pf[0] = pack8(st0, 0); pf[1] = pack8(st0, 1);
; #pragma unroll
;     for (int i = 0; i < 16; ++i) { const float e = __builtin_amdgcn_exp2f(st1[i]); st1[i] = e; sum += e; }
;     pf[2] = pack8(st1, 0); pf[3] = pack8(st1, 1);
;     l += sum;
; DI void attn_unit(const Params& p, LAS unsigned char* ldsu, int kind, int b, int h, int u, float lam) {
;     ...
;             stage(t + 3);
;             const LAS char* sp = lds + (t & 3) * SLOT_B;
;             if (t <= my_last) { bf16x8 pf[4]; attn_qk(sp + kboff, qf, pf, l); attn_pv(sp + vboff, pf, O); }
.LattnB:
	s_add_i32 s22, s21, 3
	s_min_i32 s24, s22, s6
	s_lshl_b32 s22, s24, 6
	s_add_i32 s22, s17, s22
	s_and_b32 s24, s24, 3
	s_ashr_i32 s23, s22, 31
	s_mul_i32 s24, s24, 0x9400
	s_lshl_b64 s[22:23], s[22:23], 10
	s_add_u32 s25, s16, s22
	s_addc_u32 s26, s18, s23
	s_add_u32 s27, s19, s22
	s_addc_u32 s34, s20, s23
	s_cmp_gt_i32 s21, s29
	s_cbranch_scc1 .LattnB_skip
	s_and_b32 s35, s21, 3
	s_mul_i32 s35, s35, 0x9400
	v_add_u32_e32 v0, s35, v174
	v_add_u32_e32 v14, s35, v134
	ds_read_b128 v[2:5], v0
	ds_read_b128 v[6:9], v0 offset:32
	ds_read_b128 v[10:13], v0 offset:64
	ds_read_b128 v[136:139], v0 offset:96
	ds_read_b128 v[140:143], v0 offset:8704
	ds_read_b128 v[144:147], v0 offset:8736
	ds_read_b128 v[148:151], v0 offset:8768
	ds_read_b128 v[196:199], v0 offset:8800
	ds_read_b64_tr_b16 v[200:201], v14 offset:17408
	ds_read_b64_tr_b16 v[202:203], v14 offset:19968
	ds_read_b64_tr_b16 v[204:205], v14 offset:17472
	ds_read_b64_tr_b16 v[206:207], v14 offset:20032
	ds_read_b64_tr_b16 v[208:209], v14 offset:17536
	ds_read_b64_tr_b16 v[210:211], v14 offset:20096
	ds_read_b64_tr_b16 v[212:213], v14 offset:17600
	ds_read_b64_tr_b16 v[214:215], v14 offset:20160
	ds_read_b64_tr_b16 v[216:217], v14 offset:22528
	ds_read_b64_tr_b16 v[218:219], v14 offset:25088
	ds_read_b64_tr_b16 v[220:221], v14 offset:22592
	ds_read_b64_tr_b16 v[222:223], v14 offset:25152
	ds_read_b64_tr_b16 v[224:225], v14 offset:22656
	ds_read_b64_tr_b16 v[226:227], v14 offset:25216
	ds_read_b64_tr_b16 v[228:229], v14 offset:22720
	ds_read_b64_tr_b16 v[230:231], v14 offset:25280
	ds_read_b64_tr_b16 v[232:233], v14 offset:27648
	ds_read_b64_tr_b16 v[234:235], v14 offset:30208
	ds_read_b64_tr_b16 v[236:237], v14 offset:27712
	ds_read_b64_tr_b16 v[238:239], v14 offset:30272
	ds_read_b64_tr_b16 v[240:241], v14 offset:27776
	ds_read_b64_tr_b16 v[242:243], v14 offset:30336
	ds_read_b64_tr_b16 v[244:245], v14 offset:27840
	ds_read_b64_tr_b16 v[246:247], v14 offset:30400
	ds_read_b64_tr_b16 v[248:249], v14 offset:32768
	ds_read_b64_tr_b16 v[250:251], v14 offset:35328
	ds_read_b64_tr_b16 v[156:157], v14 offset:32832
	ds_read_b64_tr_b16 v[158:159], v14 offset:35392
	ds_read_b64_tr_b16 v[160:161], v14 offset:32896
	ds_read_b64_tr_b16 v[162:163], v14 offset:35456
	ds_read_b64_tr_b16 v[164:165], v14 offset:32960
	ds_read_b64_tr_b16 v[166:167], v14 offset:35520
	s_and_b64 s[22:23], s[0:1], exec
	s_cselect_b32 s23, s26, s34
	s_cselect_b32 s22, s25, s27
	s_add_i32 s35, s24, s7
	s_mov_b32 m0, s35
	s_nop 0
	global_load_lds_dwordx4 v132, s[22:23]
	s_add_i32 s35, s24, s10
	s_addk_i32 s35, 0x400
	s_mov_b32 m0, s35
	s_nop 0
	global_load_lds_dwordx4 v131, s[22:23]
	s_and_b64 s[22:23], exec, s[8:9]
	s_cselect_b32 s23, s26, s34
	s_cselect_b32 s22, s25, s27
	s_add_i32 s35, s24, s11
	s_addk_i32 s35, 0x800
	s_mov_b32 m0, s35
	s_nop 0
	global_load_lds_dwordx4 v130, s[22:23]
	s_add_i32 s35, s24, s12
	s_addk_i32 s35, 0xc00
	s_mov_b32 m0, s35
	s_nop 0
	global_load_lds_dwordx4 v129, s[22:23]
	s_add_i32 s35, s24, s13
	s_addk_i32 s35, 0x1000
	s_mov_b32 m0, s35
	s_nop 0
	global_load_lds_dwordx4 v133, s[22:23]
	v_add_f32_e32 v15, v96, v97
	v_add_f32_e32 v15, v98, v15
	v_add_f32_e32 v15, v99, v15
	v_add_f32_e32 v15, v100, v15
	v_add_f32_e32 v15, v101, v15
	v_add_f32_e32 v15, v102, v15
	v_add_f32_e32 v15, v103, v15
	v_add_f32_e32 v15, v104, v15
	v_add_f32_e32 v15, v105, v15
	v_add_f32_e32 v15, v106, v15
	v_add_f32_e32 v15, v107, v15
	v_add_f32_e32 v15, v108, v15
	v_add_f32_e32 v15, v109, v15
	v_add_f32_e32 v15, v110, v15
	v_add_f32_e32 v15, v111, v15
	v_add_f32_e32 v15, v80, v15
	v_add_f32_e32 v15, v81, v15
	v_add_f32_e32 v15, v82, v15
	v_add_f32_e32 v15, v83, v15
	v_add_f32_e32 v15, v84, v15
	v_add_f32_e32 v15, v85, v15
	v_add_f32_e32 v15, v86, v15
	v_add_f32_e32 v15, v87, v15
	v_add_f32_e32 v15, v88, v15
	v_add_f32_e32 v15, v89, v15
	v_add_f32_e32 v15, v90, v15
	v_add_f32_e32 v15, v91, v15
	v_add_f32_e32 v15, v92, v15
	v_add_f32_e32 v15, v93, v15
	v_add_f32_e32 v15, v94, v15
	v_add_f32_e32 v15, v95, v15
	v_add_f32_e32 v175, v175, v15
	s_waitcnt vmcnt(10)
	s_waitcnt lgkmcnt(0)
	s_barrier
; #define LAS __attribute__((address_space(3)))
; DI s16x4 vtr(const LAS char* p) { return __builtin_bit_cast(s16x4, __builtin_amdgcn_ds_read_tr16_b64_v4i16((LAS v4i16_t*)p)); }
; DI bf16x8 cat4(s16x4 lo, s16x4 hi) { return __builtin_shufflevector(lo, hi, 0, 1, 2, 3, 4, 5, 6, 7); }
; #define SGB(mask, n) __builtin_amdgcn_sched_group_barrier((mask), (n), 0)
; DI void attn_qk(const LAS char* kb, const bf16x8 (&qf)[4], bf16x8 (&pf)[4], float& l) {
;     ...
;     f32x16 st0 = MFMA32(k0[0], qf[0], zero), st1 = MFMA32(k1[0], qf[0], zero);
; #pragma unroll
;     for (int s = 1; s < 4; ++s) { st0 = MFMA32(k0[s], qf[s], st0); st1 = MFMA32(k1[s], qf[s], st1); }
;     SGB(0x100, 8); SGB(0x008, 8);
;     float sum = 0.f;
; #pragma unroll
;     for (int i = 0; i < 16; ++i) { const float e = __builtin_amdgcn_exp2f(st0[i]); st0[i] = e; sum += e; }
;     pf[0] = pack8(st0, 0); pf[1] = pack8(st0, 1);
; #pragma unroll
;     for (int i = 0; i < 16; ++i) { const float e = __builtin_amdgcn_exp2f(st1[i]); st1[i] = e; sum += e; }
;     pf[2] = pack8(st1, 0); pf[3] = pack8(st1, 1);
;     l += sum;
; }
; DI void attn_pv(const LAS char* vb, const bf16x8 (&pf)[4], f32x16 (&O)[4]) {
;     s16x4 va[8], vc[8];
; #pragma unroll
;     for (int ks = 0; ks < 4; ++ks) { va[2 * ks] = vtr(vb + ks * 16 * VRS); va[2 * ks + 1] = vtr(vb + (ks * 16 + 8) * VRS); }
; #pragma unroll
;     for (int ks = 0; ks < 4; ++ks) { vc[2 * ks] = vtr(vb + ks * 16 * VRS + 64); vc[2 * ks + 1] = vtr(vb + (ks * 16 + 8) * VRS + 64); }
; #pragma unroll
;     for (int ks = 0; ks < 4; ++ks) O[0] = MFMA32(cat4(va[2 * ks], va[2 * ks + 1]), pf[ks], O[0]);
; #pragma unroll
;     for (int ks = 0; ks < 4; ++ks) { va[2 * ks] = vtr(vb + ks * 16 * VRS + 128); va[2 * ks + 1] = vtr(vb + (ks * 16 + 8) * VRS + 128); }
;     SGB(0x100, 16); SGB(0x008, 4); SGB(0x100, 8);
; #pragma unroll
;     for (int ks = 0; ks < 4; ++ks) O[1] = MFMA32(cat4(vc[2 * ks], vc[2 * ks + 1]), pf[ks], O[1]);
; #pragma unroll
;     for (int ks = 0; ks < 4; ++ks) { vc[2 * ks] = vtr(vb + ks * 16 * VRS + 192); vc[2 * ks + 1] = vtr(vb + (ks * 16 + 8) * VRS + 192); }
;     SGB(0x008, 4); SGB(0x100, 8);
; #pragma unroll
;     for (int ks = 0; ks < 4; ++ks) O[2] = MFMA32(cat4(va[2 * ks], va[2 * ks + 1]), pf[ks], O[2]);
;     SGB(0x008, 4);
; #pragma unroll
;     for (int ks = 0; ks < 4; ++ks) O[3] = MFMA32(cat4(vc[2 * ks], vc[2 * ks + 1]), pf[ks], O[3]);
;     SGB(0x008, 4);
	v_mfma_f32_32x32x16_bf16 v[96:111], v[2:5], v[112:115], 0
	v_mfma_f32_32x32x16_bf16 v[96:111], v[6:9], v[116:119], v[96:111]
	v_mfma_f32_32x32x16_bf16 v[96:111], v[10:13], v[120:123], v[96:111]
	v_mfma_f32_32x32x16_bf16 v[96:111], v[136:139], v[124:127], v[96:111]
	s_nop 7
	s_nop 2
	v_mfma_f32_32x32x16_bf16 v[80:95], v[140:143], v[112:115], 0
	v_exp_f32_e32 v96, v96
	v_exp_f32_e32 v97, v97
	v_mfma_f32_32x32x16_bf16 v[80:95], v[144:147], v[116:119], v[80:95]
	v_exp_f32_e32 v98, v98
	v_exp_f32_e32 v99, v99
	v_cvt_pk_bf16_f32 v2, v96, v97
	v_mfma_f32_32x32x16_bf16 v[80:95], v[148:151], v[120:123], v[80:95]
	v_exp_f32_e32 v100, v100
	v_exp_f32_e32 v101, v101
	v_cvt_pk_bf16_f32 v3, v98, v99
	v_mfma_f32_32x32x16_bf16 v[80:95], v[196:199], v[124:127], v[80:95]
	v_exp_f32_e32 v102, v102
	v_exp_f32_e32 v103, v103
	v_cvt_pk_bf16_f32 v4, v100, v101
	v_cvt_pk_bf16_f32 v5, v102, v103
	s_nop 1
	v_mfma_f32_32x32x16_bf16 v[64:79], v[200:203], v[2:5], v[64:79]
	v_exp_f32_e32 v104, v104
	v_exp_f32_e32 v105, v105
	v_mfma_f32_32x32x16_bf16 v[48:63], v[204:207], v[2:5], v[48:63]
	v_exp_f32_e32 v106, v106
	v_exp_f32_e32 v107, v107
	v_cvt_pk_bf16_f32 v6, v104, v105
	v_mfma_f32_32x32x16_bf16 v[32:47], v[208:211], v[2:5], v[32:47]
	v_exp_f32_e32 v108, v108
	v_exp_f32_e32 v109, v109
	v_cvt_pk_bf16_f32 v7, v106, v107
	v_mfma_f32_32x32x16_bf16 v[16:31], v[212:215], v[2:5], v[16:31]
	v_exp_f32_e32 v110, v110
	v_exp_f32_e32 v111, v111
	v_cvt_pk_bf16_f32 v8, v108, v109
	v_cvt_pk_bf16_f32 v9, v110, v111
	s_nop 1
	v_mfma_f32_32x32x16_bf16 v[64:79], v[216:219], v[6:9], v[64:79]
	v_exp_f32_e32 v80, v80
	v_exp_f32_e32 v81, v81
	v_mfma_f32_32x32x16_bf16 v[48:63], v[220:223], v[6:9], v[48:63]
	v_exp_f32_e32 v82, v82
	v_exp_f32_e32 v83, v83
	v_cvt_pk_bf16_f32 v140, v80, v81
	v_mfma_f32_32x32x16_bf16 v[32:47], v[224:227], v[6:9], v[32:47]
	v_exp_f32_e32 v84, v84
	v_exp_f32_e32 v85, v85
	v_cvt_pk_bf16_f32 v141, v82, v83
	v_mfma_f32_32x32x16_bf16 v[16:31], v[228:231], v[6:9], v[16:31]
	v_exp_f32_e32 v86, v86
	v_exp_f32_e32 v87, v87
	v_cvt_pk_bf16_f32 v142, v84, v85
	v_cvt_pk_bf16_f32 v143, v86, v87
	s_nop 1
	v_mfma_f32_32x32x16_bf16 v[64:79], v[232:235], v[140:143], v[64:79]
	v_exp_f32_e32 v88, v88
	v_exp_f32_e32 v89, v89
	v_mfma_f32_32x32x16_bf16 v[48:63], v[236:239], v[140:143], v[48:63]
	v_exp_f32_e32 v90, v90
	v_exp_f32_e32 v91, v91
	v_cvt_pk_bf16_f32 v144, v88, v89
	v_mfma_f32_32x32x16_bf16 v[32:47], v[240:243], v[140:143], v[32:47]
	v_exp_f32_e32 v92, v92
	v_exp_f32_e32 v93, v93
	v_cvt_pk_bf16_f32 v145, v90, v91
	v_mfma_f32_32x32x16_bf16 v[16:31], v[244:247], v[140:143], v[16:31]
	v_exp_f32_e32 v94, v94
	v_exp_f32_e32 v95, v95
	v_cvt_pk_bf16_f32 v146, v92, v93
	v_cvt_pk_bf16_f32 v147, v94, v95
	s_nop 1
	v_mfma_f32_32x32x16_bf16 v[64:79], v[248:251], v[144:147], v[64:79]
	v_mfma_f32_32x32x16_bf16 v[48:63], v[156:159], v[144:147], v[48:63]
	v_mfma_f32_32x32x16_bf16 v[32:47], v[160:163], v[144:147], v[32:47]
	v_mfma_f32_32x32x16_bf16 v[16:31], v[164:167], v[144:147], v[16:31]
	s_barrier
	s_branch .LBB0_744

; DI void attn_qk(const LAS char* kb, const bf16x8 (&qf)[4], bf16x8 (&pf)[4], float& l) {
;     ...
;     float sum = 0.f;
; #pragma unroll
;     for (int i = 0; i < 16; ++i) { const float e = __builtin_amdgcn_exp2f(st0[i]); st0[i] = e; sum += e; }
;     pf[0] = pack8(st0, 0); pf[1] = pack8(st0, 1);
; #pragma unroll
;     for (int i = 0; i < 16; ++i) { const float e = __builtin_amdgcn_exp2f(st1[i]); st1[i] = e; sum += e; }
;     pf[2] = pack8(st1, 0); pf[3] = pack8(st1, 1);
;     l += sum;
.Lattn_exit:
	v_add_f32_e32 v15, v96, v97
	v_add_f32_e32 v15, v98, v15
	v_add_f32_e32 v15, v99, v15
	v_add_f32_e32 v15, v100, v15
	v_add_f32_e32 v15, v101, v15
	v_add_f32_e32 v15, v102, v15
	v_add_f32_e32 v15, v103, v15
	v_add_f32_e32 v15, v104, v15
	v_add_f32_e32 v15, v105, v15
	v_add_f32_e32 v15, v106, v15
	v_add_f32_e32 v15, v107, v15
	v_add_f32_e32 v15, v108, v15
	v_add_f32_e32 v15, v109, v15
	v_add_f32_e32 v15, v110, v15
	v_add_f32_e32 v15, v111, v15
	v_add_f32_e32 v15, v80, v15
	v_add_f32_e32 v15, v81, v15
	v_add_f32_e32 v15, v82, v15
	v_add_f32_e32 v15, v83, v15
	v_add_f32_e32 v15, v84, v15
	v_add_f32_e32 v15, v85, v15
	v_add_f32_e32 v15, v86, v15
	v_add_f32_e32 v15, v87, v15
	v_add_f32_e32 v15, v88, v15
	v_add_f32_e32 v15, v89, v15
	v_add_f32_e32 v15, v90, v15
	v_add_f32_e32 v15, v91, v15
	v_add_f32_e32 v15, v92, v15
	v_add_f32_e32 v15, v93, v15
	v_add_f32_e32 v15, v94, v15
	v_add_f32_e32 v15, v95, v15
	v_add_f32_e32 v175, v175, v15
	s_and_b64 vcc, exec, s[0:1]
	s_cbranch_vccz .LBB0_747
	s_barrier
	s_branch .LBB0_747
